# GU1 phase: the two CUs that run the memory K/V GEMM tiles no longer take a share of the weight conversion
# baseline (speedup 1.0000x reference)
.LBB0_402:
	s_mov_b32 s4, s70
	s_mov_b32 s5, s67
	v_sub_co_u32_e64 v4, s[0:1], s4, 2
	v_writelane_b32 v247, s4, 32
	s_xor_b64 s[42:43], s[0:1], -1
	s_lshl_b32 s46, s4, 10
	v_writelane_b32 v247, s5, 33
	s_lshl_b32 s4, s11, 1
	v_readlane_b32 s22, v247, 26
	s_mul_hi_u32 s1, s70, 0xb00000
	s_mul_i32 s0, s70, 0xb00000
	s_cmp_lt_i32 s4, s50
	s_mov_b32 s47, s67
	v_readlane_b32 s23, v247, 27
	s_cbranch_scc1 .LBB0_753
	s_add_i32 s5, s11, 2
	s_cmp_ge_i32 s5, s50
	s_cbranch_scc1 .LBB0_753
	s_sub_i32 s31, s31, 16
	v_readlane_b32 s5, v248, 4
	s_sub_i32 s5, s11, s5
	s_ashr_i32 s4, s14, 6
	s_lshl_b32 s5, s5, 3
	v_and_b32_e32 v0, 63, v165
	s_add_i32 s11, s5, s4
	s_lshl_b32 s4, s4, 14
	s_add_i32 s10, s4, 0
	s_waitcnt vmcnt(8)
	v_and_b32_e32 v46, 31, v165
	v_lshrrev_b32_e32 v47, 5, v0
	s_waitcnt vmcnt(7)
	v_lshrrev_b32_e32 v48, 3, v0
	v_lshlrev_b32_e32 v0, 3, v0
	s_cmpk_gt_i32 s11, 0x57f
	v_lshl_add_u32 v49, v46, 2, s10
	s_waitcnt vmcnt(6)
	v_and_b32_e32 v52, 56, v0
	v_lshlrev_b32_e32 v51, 2, v48
	v_mul_u32_u24_e32 v50, 0x84, v47
	s_cbranch_scc1 .LBB0_470
	global_load_dwordx2 v[0:1], v161, s[8:9] offset:2088
	v_lshlrev_b32_e32 v160, 1, v52
	v_lshl_add_u64 v[2:3], s[8:9], 0, v[160:161]
	s_mov_b64 s[4:5], 0x1300000
	v_lshl_add_u64 v[2:3], v[2:3], 0, s[4:5]
	s_mul_i32 s4, s11, 0x16000
	v_mul_u32_u24_e32 v5, 0x84, v52
	v_mov_b32_e32 v6, s4
	s_movk_i32 s3, 0xb00
	v_add3_u32 v5, s10, v5, v51
	v_mad_u32_u24 v10, v48, s3, v6
	v_lshl_or_b32 v11, s11, 5, v46
	s_lshl_b32 s14, s31, 5
	v_add_u32_e32 v12, v49, v50
	s_mov_b32 s15, s11
	s_waitcnt vmcnt(0)
	v_lshl_add_u64 v[0:1], v[0:1], 0, s[0:1]
	s_branch .LBB0_406
